# v032 with all per-segment s_setprio flips in the four GEMM K-loops deleted (timing-only edit)
# speedup vs baseline: 1.0204x; 1.0031x over previous
.LBB0_233:
	s_add_u32 s6, s18, 0xfffc0080
	s_addc_u32 s33, s19, -1
	s_add_i32 s94, 0, 0x10000
	s_cmp_eq_u32 vcc_hi, 12
	s_cselect_b32 s79, s15, s33
	s_cselect_b32 s78, s17, s6
	s_cselect_b32 s77, s24, vcc_lo
	s_cselect_b32 s76, s69, s71
	s_add_i32 s6, 0, 0x14000
	v_add_u32_e32 v36, s94, v184
	v_add_u32_e32 v168, s6, v184
	ds_read_b128 v[20:23], v36
	ds_read_b128 v[24:27], v36 offset:1024
	ds_read_b128 v[28:31], v36 offset:2048
	ds_read_b128 v[36:39], v36 offset:3072
	ds_read_b128 v[158:161], v168
	ds_read_b128 v[162:165], v168 offset:1024
	ds_read_b128 v[174:177], v168 offset:2048
	ds_read_b128 v[178:181], v168 offset:3072
	v_lshl_add_u64 v[168:169], s[18:19], 0, v[154:155]
	s_add_i32 m0, s35, 0xc000
	ds_read_b128 v[208:211], v206
	ds_read_b128 v[212:215], v206 offset:1024
	ds_read_b128 v[216:219], v206 offset:2048
	ds_read_b128 v[220:223], v206 offset:3072
	ds_read_b128 v[224:227], v206 offset:4096
	ds_read_b128 v[228:231], v206 offset:5120
	ds_read_b128 v[232:235], v206 offset:6144
	ds_read_b128 v[236:239], v206 offset:7168
	global_load_lds_dwordx4 v[168:169], off
	v_lshl_add_u64 v[168:169], s[18:19], 0, v[156:157]
	s_add_i32 m0, s35, 0xe000
	s_nop 0
	global_load_lds_dwordx4 v[168:169], off
	s_waitcnt vmcnt(8)
	s_waitcnt lgkmcnt(0)
	s_barrier
	s_waitcnt lgkmcnt(0)
	v_mfma_f32_16x16x32_bf16 v[144:147], v[20:23], v[208:211], v[144:147]
	v_mfma_f32_16x16x32_bf16 v[140:143], v[28:31], v[208:211], v[140:143]
	v_mfma_f32_16x16x32_bf16 v[128:131], v[20:23], v[216:219], v[128:131]
	v_mfma_f32_16x16x32_bf16 v[124:127], v[28:31], v[216:219], v[124:127]
	v_mfma_f32_16x16x32_bf16 v[112:115], v[20:23], v[224:227], v[112:115]
	v_mfma_f32_16x16x32_bf16 v[108:111], v[28:31], v[224:227], v[108:111]
	v_mfma_f32_16x16x32_bf16 v[96:99], v[20:23], v[232:235], v[96:99]
	v_mfma_f32_16x16x32_bf16 v[92:95], v[28:31], v[232:235], v[92:95]
	v_mfma_f32_16x16x32_bf16 v[144:147], v[24:27], v[212:215], v[144:147]
	v_mfma_f32_16x16x32_bf16 v[140:143], v[36:39], v[212:215], v[140:143]
	v_mfma_f32_16x16x32_bf16 v[128:131], v[24:27], v[220:223], v[128:131]
	v_mfma_f32_16x16x32_bf16 v[124:127], v[36:39], v[220:223], v[124:127]
	v_mfma_f32_16x16x32_bf16 v[112:115], v[24:27], v[228:231], v[112:115]
	v_mfma_f32_16x16x32_bf16 v[108:111], v[36:39], v[228:231], v[108:111]
	v_mfma_f32_16x16x32_bf16 v[96:99], v[24:27], v[236:239], v[96:99]
	v_mfma_f32_16x16x32_bf16 v[92:95], v[36:39], v[236:239], v[92:95]
	v_mfma_f32_16x16x32_bf16 v[136:139], v[158:161], v[208:211], v[136:139]
	v_mfma_f32_16x16x32_bf16 v[132:135], v[174:177], v[208:211], v[132:135]
	v_mfma_f32_16x16x32_bf16 v[120:123], v[158:161], v[216:219], v[120:123]
	v_mfma_f32_16x16x32_bf16 v[116:119], v[174:177], v[216:219], v[116:119]
	v_mfma_f32_16x16x32_bf16 v[104:107], v[158:161], v[224:227], v[104:107]
	v_mfma_f32_16x16x32_bf16 v[100:103], v[174:177], v[224:227], v[100:103]
	v_mfma_f32_16x16x32_bf16 v[88:91], v[158:161], v[232:235], v[88:91]
	v_mfma_f32_16x16x32_bf16 v[84:87], v[174:177], v[232:235], v[84:87]
	v_mfma_f32_16x16x32_bf16 v[136:139], v[162:165], v[212:215], v[136:139]
	v_mfma_f32_16x16x32_bf16 v[132:135], v[178:181], v[212:215], v[132:135]
	v_mfma_f32_16x16x32_bf16 v[120:123], v[162:165], v[220:223], v[120:123]
	v_mfma_f32_16x16x32_bf16 v[116:119], v[178:181], v[220:223], v[116:119]
	v_mfma_f32_16x16x32_bf16 v[104:107], v[162:165], v[228:231], v[104:107]
	v_mfma_f32_16x16x32_bf16 v[100:103], v[178:181], v[228:231], v[100:103]
	v_mfma_f32_16x16x32_bf16 v[88:91], v[162:165], v[236:239], v[88:91]
	v_mfma_f32_16x16x32_bf16 v[84:87], v[178:181], v[236:239], v[84:87]
	s_barrier
	s_add_i32 s33, s94, s57
	v_lshl_add_u64 v[168:169], s[76:77], 0, v[2:3]
	s_mov_b32 m0, s33
	ds_read_b128 v[208:211], v206 offset:16384
	ds_read_b128 v[212:215], v206 offset:17408
	ds_read_b128 v[216:219], v206 offset:18432
	ds_read_b128 v[220:223], v206 offset:19456
	ds_read_b128 v[224:227], v206 offset:20480
	ds_read_b128 v[228:231], v206 offset:21504
	ds_read_b128 v[232:235], v206 offset:22528
	ds_read_b128 v[236:239], v206 offset:23552
	global_load_lds_dwordx4 v[168:169], off
	s_add_i32 m0, s33, 0x2000
	s_add_u32 s94, s76, 0x40000
	v_lshl_add_u64 v[170:171], s[76:77], 0, v[152:153]
	s_addc_u32 s95, s77, 0
	s_add_i32 s6, s6, s57
	global_load_lds_dwordx4 v[170:171], off
	v_lshl_add_u64 v[182:183], s[94:95], 0, v[2:3]
	s_mov_b32 m0, s6
	v_lshl_add_u64 v[240:241], s[78:79], 0, v[150:151]
	global_load_lds_dwordx4 v[182:183], off
	v_lshl_add_u64 v[182:183], s[94:95], 0, v[152:153]
	s_add_i32 m0, s6, 0x2000
	s_nop 0
	global_load_lds_dwordx4 v[182:183], off
	v_lshl_add_u64 v[182:183], s[78:79], 0, v[148:149]
	s_mov_b32 m0, s35
	s_nop 0
	global_load_lds_dwordx4 v[182:183], off
	s_mov_b32 m0, s9
	s_nop 0
	global_load_lds_dwordx4 v[240:241], off
	s_waitcnt vmcnt(8)
	s_waitcnt lgkmcnt(0)
	s_barrier
	s_waitcnt lgkmcnt(0)
	v_mfma_f32_16x16x32_bf16 v[80:83], v[20:23], v[208:211], v[80:83]
	v_mfma_f32_16x16x32_bf16 v[76:79], v[28:31], v[208:211], v[76:79]
	v_mfma_f32_16x16x32_bf16 v[64:67], v[20:23], v[216:219], v[64:67]
	v_mfma_f32_16x16x32_bf16 v[60:63], v[28:31], v[216:219], v[60:63]
	v_mfma_f32_16x16x32_bf16 v[48:51], v[20:23], v[224:227], v[48:51]
	v_mfma_f32_16x16x32_bf16 v[44:47], v[28:31], v[224:227], v[44:47]
	v_mfma_f32_16x16x32_bf16 v[16:19], v[20:23], v[232:235], v[16:19]
	v_mfma_f32_16x16x32_bf16 v[12:15], v[28:31], v[232:235], v[12:15]
	v_mfma_f32_16x16x32_bf16 v[80:83], v[24:27], v[212:215], v[80:83]
	v_mfma_f32_16x16x32_bf16 v[76:79], v[36:39], v[212:215], v[76:79]
	v_mfma_f32_16x16x32_bf16 v[64:67], v[24:27], v[220:223], v[64:67]
	v_mfma_f32_16x16x32_bf16 v[60:63], v[36:39], v[220:223], v[60:63]
	v_mfma_f32_16x16x32_bf16 v[48:51], v[24:27], v[228:231], v[48:51]
	v_mfma_f32_16x16x32_bf16 v[44:47], v[36:39], v[228:231], v[44:47]
	v_mfma_f32_16x16x32_bf16 v[16:19], v[24:27], v[236:239], v[16:19]
	v_mfma_f32_16x16x32_bf16 v[12:15], v[36:39], v[236:239], v[12:15]
	v_mfma_f32_16x16x32_bf16 v[40:43], v[158:161], v[224:227], v[40:43]
	v_mfma_f32_16x16x32_bf16 v[32:35], v[174:177], v[224:227], v[32:35]
	v_mfma_f32_16x16x32_bf16 v[8:11], v[158:161], v[232:235], v[8:11]
	v_mfma_f32_16x16x32_bf16 v[4:7], v[174:177], v[232:235], v[4:7]
	v_mfma_f32_16x16x32_bf16 v[20:23], v[158:161], v[208:211], v[72:75]
	v_mfma_f32_16x16x32_bf16 v[24:27], v[174:177], v[208:211], v[68:71]
	v_mfma_f32_16x16x32_bf16 v[28:31], v[158:161], v[216:219], v[56:59]
	v_mfma_f32_16x16x32_bf16 v[36:39], v[174:177], v[216:219], v[52:55]
	v_mfma_f32_16x16x32_bf16 v[40:43], v[162:165], v[228:231], v[40:43]
	v_mfma_f32_16x16x32_bf16 v[32:35], v[178:181], v[228:231], v[32:35]
	v_mfma_f32_16x16x32_bf16 v[8:11], v[162:165], v[236:239], v[8:11]
	v_mfma_f32_16x16x32_bf16 v[4:7], v[178:181], v[236:239], v[4:7]
	v_mfma_f32_16x16x32_bf16 v[20:23], v[162:165], v[212:215], v[20:23]
	v_mfma_f32_16x16x32_bf16 v[24:27], v[178:181], v[212:215], v[24:27]
	v_mfma_f32_16x16x32_bf16 v[28:31], v[162:165], v[220:223], v[28:31]
	v_mfma_f32_16x16x32_bf16 v[36:39], v[178:181], v[220:223], v[36:39]
	s_barrier
	s_add_i32 s6, 0, 0x18000
	s_add_i32 s33, 0, 0x1c000
	v_add_u32_e32 v72, s6, v184
	v_add_u32_e32 v178, s33, v184
	ds_read_b128 v[52:55], v72
	ds_read_b128 v[56:59], v72 offset:1024
	ds_read_b128 v[68:71], v72 offset:2048
	ds_read_b128 v[72:75], v72 offset:3072
	ds_read_b128 v[158:161], v178
	ds_read_b128 v[162:165], v178 offset:1024
	ds_read_b128 v[174:177], v178 offset:2048
	ds_read_b128 v[178:181], v178 offset:3072
	s_add_u32 s78, s78, 0x40000
	s_addc_u32 s79, s79, 0
	s_mov_b32 m0, s4
	v_lshl_add_u64 v[242:243], s[78:79], 0, v[148:149]
	ds_read_b128 v[208:211], v206 offset:32768
	ds_read_b128 v[212:215], v206 offset:33792
	ds_read_b128 v[216:219], v206 offset:34816
	ds_read_b128 v[220:223], v206 offset:35840
	ds_read_b128 v[224:227], v206 offset:36864
	ds_read_b128 v[228:231], v206 offset:37888
	ds_read_b128 v[232:235], v206 offset:38912
	ds_read_b128 v[236:239], v206 offset:39936
	global_load_lds_dwordx4 v[242:243], off
	v_lshl_add_u64 v[242:243], s[78:79], 0, v[150:151]
	s_mov_b32 m0, s20
	s_nop 0
	global_load_lds_dwordx4 v[242:243], off
	s_waitcnt vmcnt(8)
	s_waitcnt lgkmcnt(0)
	s_barrier
	s_waitcnt lgkmcnt(0)
	v_mfma_f32_16x16x32_bf16 v[144:147], v[52:55], v[208:211], v[144:147]
	v_mfma_f32_16x16x32_bf16 v[140:143], v[68:71], v[208:211], v[140:143]
	v_mfma_f32_16x16x32_bf16 v[128:131], v[52:55], v[216:219], v[128:131]
	v_mfma_f32_16x16x32_bf16 v[124:127], v[68:71], v[216:219], v[124:127]
	v_mfma_f32_16x16x32_bf16 v[112:115], v[52:55], v[224:227], v[112:115]
	v_mfma_f32_16x16x32_bf16 v[108:111], v[68:71], v[224:227], v[108:111]
	v_mfma_f32_16x16x32_bf16 v[96:99], v[52:55], v[232:235], v[96:99]
	v_mfma_f32_16x16x32_bf16 v[92:95], v[68:71], v[232:235], v[92:95]
	v_mfma_f32_16x16x32_bf16 v[144:147], v[56:59], v[212:215], v[144:147]
	v_mfma_f32_16x16x32_bf16 v[140:143], v[72:75], v[212:215], v[140:143]
	v_mfma_f32_16x16x32_bf16 v[128:131], v[56:59], v[220:223], v[128:131]
	v_mfma_f32_16x16x32_bf16 v[124:127], v[72:75], v[220:223], v[124:127]
	v_mfma_f32_16x16x32_bf16 v[112:115], v[56:59], v[228:231], v[112:115]
	v_mfma_f32_16x16x32_bf16 v[108:111], v[72:75], v[228:231], v[108:111]
	v_mfma_f32_16x16x32_bf16 v[96:99], v[56:59], v[236:239], v[96:99]
	v_mfma_f32_16x16x32_bf16 v[92:95], v[72:75], v[236:239], v[92:95]
	v_mfma_f32_16x16x32_bf16 v[136:139], v[158:161], v[208:211], v[136:139]
	v_mfma_f32_16x16x32_bf16 v[132:135], v[174:177], v[208:211], v[132:135]
	v_mfma_f32_16x16x32_bf16 v[120:123], v[158:161], v[216:219], v[120:123]
	v_mfma_f32_16x16x32_bf16 v[116:119], v[174:177], v[216:219], v[116:119]
	v_mfma_f32_16x16x32_bf16 v[104:107], v[158:161], v[224:227], v[104:107]
	v_mfma_f32_16x16x32_bf16 v[100:103], v[174:177], v[224:227], v[100:103]
	v_mfma_f32_16x16x32_bf16 v[88:91], v[158:161], v[232:235], v[88:91]
	v_mfma_f32_16x16x32_bf16 v[84:87], v[174:177], v[232:235], v[84:87]
	v_mfma_f32_16x16x32_bf16 v[136:139], v[162:165], v[212:215], v[136:139]
	v_mfma_f32_16x16x32_bf16 v[132:135], v[178:181], v[212:215], v[132:135]
	v_mfma_f32_16x16x32_bf16 v[120:123], v[162:165], v[220:223], v[120:123]
	v_mfma_f32_16x16x32_bf16 v[116:119], v[178:181], v[220:223], v[116:119]
	v_mfma_f32_16x16x32_bf16 v[104:107], v[162:165], v[228:231], v[104:107]
	v_mfma_f32_16x16x32_bf16 v[100:103], v[178:181], v[228:231], v[100:103]
	v_mfma_f32_16x16x32_bf16 v[88:91], v[162:165], v[236:239], v[88:91]
	v_mfma_f32_16x16x32_bf16 v[84:87], v[178:181], v[236:239], v[84:87]
	s_barrier
	s_add_i32 s6, s6, s57
	v_lshl_add_u64 v[168:169], v[168:169], 0, s[30:31]
	s_mov_b32 m0, s6
	ds_read_b128 v[208:211], v206 offset:49152
	ds_read_b128 v[212:215], v206 offset:50176
	ds_read_b128 v[216:219], v206 offset:51200
	ds_read_b128 v[220:223], v206 offset:52224
	ds_read_b128 v[224:227], v206 offset:53248
	ds_read_b128 v[228:231], v206 offset:54272
	ds_read_b128 v[232:235], v206 offset:55296
	ds_read_b128 v[236:239], v206 offset:56320
	global_load_lds_dwordx4 v[168:169], off
	s_add_i32 m0, s6, 0x2000
	s_add_u32 s76, s76, 0x40080
	v_lshl_add_u64 v[168:169], v[170:171], 0, s[30:31]
	s_addc_u32 s77, s77, 0
	s_add_i32 s6, s33, s57
	global_load_lds_dwordx4 v[168:169], off
	v_lshl_add_u64 v[168:169], s[76:77], 0, v[2:3]
	s_mov_b32 m0, s6
	s_nop 0
	global_load_lds_dwordx4 v[168:169], off
	v_lshl_add_u64 v[168:169], s[76:77], 0, v[152:153]
	s_add_i32 m0, s6, 0x2000
	s_nop 0
	global_load_lds_dwordx4 v[168:169], off
	v_lshl_add_u64 v[168:169], v[182:183], 0, s[30:31]
	s_mov_b32 m0, s82
	s_nop 0
	global_load_lds_dwordx4 v[168:169], off
	v_lshl_add_u64 v[168:169], v[240:241], 0, s[30:31]
	s_mov_b32 m0, s27
	s_nop 0
	global_load_lds_dwordx4 v[168:169], off
	s_waitcnt vmcnt(8)
	s_waitcnt lgkmcnt(0)
	s_barrier
	s_waitcnt lgkmcnt(0)
	v_mfma_f32_16x16x32_bf16 v[80:83], v[52:55], v[208:211], v[80:83]
	v_mfma_f32_16x16x32_bf16 v[76:79], v[68:71], v[208:211], v[76:79]
	v_mfma_f32_16x16x32_bf16 v[64:67], v[52:55], v[216:219], v[64:67]
	v_mfma_f32_16x16x32_bf16 v[60:63], v[68:71], v[216:219], v[60:63]
	v_mfma_f32_16x16x32_bf16 v[48:51], v[52:55], v[224:227], v[48:51]
	v_mfma_f32_16x16x32_bf16 v[44:47], v[68:71], v[224:227], v[44:47]
	v_mfma_f32_16x16x32_bf16 v[16:19], v[52:55], v[232:235], v[16:19]
	v_mfma_f32_16x16x32_bf16 v[12:15], v[68:71], v[232:235], v[12:15]
	v_mfma_f32_16x16x32_bf16 v[80:83], v[56:59], v[212:215], v[80:83]
	v_mfma_f32_16x16x32_bf16 v[76:79], v[72:75], v[212:215], v[76:79]
	v_mfma_f32_16x16x32_bf16 v[64:67], v[56:59], v[220:223], v[64:67]
	v_mfma_f32_16x16x32_bf16 v[60:63], v[72:75], v[220:223], v[60:63]
	v_mfma_f32_16x16x32_bf16 v[48:51], v[56:59], v[228:231], v[48:51]
	v_mfma_f32_16x16x32_bf16 v[44:47], v[72:75], v[228:231], v[44:47]
	v_mfma_f32_16x16x32_bf16 v[16:19], v[56:59], v[236:239], v[16:19]
	v_mfma_f32_16x16x32_bf16 v[12:15], v[72:75], v[236:239], v[12:15]
	v_mfma_f32_16x16x32_bf16 v[20:23], v[158:161], v[208:211], v[20:23]
	v_mfma_f32_16x16x32_bf16 v[72:75], v[162:165], v[212:215], v[20:23]
	v_mfma_f32_16x16x32_bf16 v[20:23], v[174:177], v[208:211], v[24:27]
	v_mfma_f32_16x16x32_bf16 v[68:71], v[178:181], v[212:215], v[20:23]
	v_mfma_f32_16x16x32_bf16 v[20:23], v[158:161], v[216:219], v[28:31]
	v_mfma_f32_16x16x32_bf16 v[56:59], v[162:165], v[220:223], v[20:23]
	v_mfma_f32_16x16x32_bf16 v[20:23], v[174:177], v[216:219], v[36:39]
	v_mfma_f32_16x16x32_bf16 v[52:55], v[178:181], v[220:223], v[20:23]
	v_mfma_f32_16x16x32_bf16 v[20:23], v[158:161], v[224:227], v[40:43]
	v_mfma_f32_16x16x32_bf16 v[40:43], v[162:165], v[228:231], v[20:23]
	v_mfma_f32_16x16x32_bf16 v[20:23], v[174:177], v[224:227], v[32:35]
	v_mfma_f32_16x16x32_bf16 v[8:11], v[158:161], v[232:235], v[8:11]
	v_mfma_f32_16x16x32_bf16 v[4:7], v[174:177], v[232:235], v[4:7]
	v_mfma_f32_16x16x32_bf16 v[32:35], v[178:181], v[228:231], v[20:23]
	v_mfma_f32_16x16x32_bf16 v[8:11], v[162:165], v[236:239], v[8:11]
	v_mfma_f32_16x16x32_bf16 v[4:7], v[178:181], v[236:239], v[4:7]
	s_barrier
	s_add_i32 vcc_hi, vcc_hi, 2
	s_add_u32 s18, s18, 0x100
	s_addc_u32 s19, s19, 0
	s_add_u32 s71, s71, 0x100
	s_addc_u32 vcc_lo, vcc_lo, 0
	s_cmp_gt_u32 vcc_hi, 13
	s_cbranch_scc0 .LBB0_233
	s_and_b64 vcc, exec, s[66:67]
	s_cbranch_vccz .LBB0_236
	s_barrier

.LBB0_604:
	s_add_u32 s33, s64, s12
	s_addc_u32 s70, s65, s13
	s_add_u32 s33, s33, 0x100
	s_addc_u32 s70, s70, 0
	s_add_u32 s79, s75, s12
	s_addc_u32 s71, s76, s13
	s_add_i32 s80, 0, 0x10000
	s_cmpk_eq_i32 s12, 0x700
	s_cselect_b32 s73, s63, s70
	s_cselect_b32 s72, s77, s33
	v_add_u32_e32 v159, s80, v156
	s_cselect_b32 s71, s61, s71
	s_cselect_b32 s70, s78, s79
	s_add_i32 s33, 0, 0x14000
	ds_read_b128 v[160:163], v159
	ds_read_b128 v[168:171], v159 offset:1024
	ds_read_b128 v[174:177], v159 offset:2048
	ds_read_b128 v[178:181], v159 offset:3072
	v_add_u32_e32 v159, s33, v156
	ds_read_b128 v[182:185], v159
	ds_read_b128 v[186:189], v159 offset:1024
	ds_read_b128 v[200:203], v159 offset:2048
	ds_read_b128 v[204:207], v159 offset:3072
	v_lshl_add_u64 v[164:165], v[142:143], 0, s[12:13]
	s_add_i32 m0, s3, 0xc000
	ds_read_b128 v[208:211], v158
	ds_read_b128 v[212:215], v158 offset:1024
	ds_read_b128 v[216:219], v158 offset:2048
	ds_read_b128 v[220:223], v158 offset:3072
	ds_read_b128 v[224:227], v158 offset:4096
	ds_read_b128 v[228:231], v158 offset:5120
	ds_read_b128 v[232:235], v158 offset:6144
	ds_read_b128 v[236:239], v158 offset:7168
	global_load_lds_dwordx4 v[164:165], off
	v_lshl_add_u64 v[164:165], v[144:145], 0, s[12:13]
	s_add_i32 m0, s3, 0xe000
	s_nop 0
	global_load_lds_dwordx4 v[164:165], off
	s_waitcnt vmcnt(8)
	s_waitcnt lgkmcnt(0)
	s_barrier
	s_waitcnt lgkmcnt(0)
	v_mfma_f32_16x16x32_bf16 v[128:131], v[160:163], v[208:211], v[128:131]
	v_mfma_f32_16x16x32_bf16 v[124:127], v[174:177], v[208:211], v[124:127]
	v_mfma_f32_16x16x32_bf16 v[112:115], v[160:163], v[216:219], v[112:115]
	v_mfma_f32_16x16x32_bf16 v[108:111], v[174:177], v[216:219], v[108:111]
	v_mfma_f32_16x16x32_bf16 v[88:91], v[160:163], v[224:227], v[88:91]
	v_mfma_f32_16x16x32_bf16 v[96:99], v[174:177], v[224:227], v[96:99]
	v_mfma_f32_16x16x32_bf16 v[80:83], v[160:163], v[232:235], v[80:83]
	v_mfma_f32_16x16x32_bf16 v[76:79], v[174:177], v[232:235], v[76:79]
	v_mfma_f32_16x16x32_bf16 v[128:131], v[168:171], v[212:215], v[128:131]
	v_mfma_f32_16x16x32_bf16 v[124:127], v[178:181], v[212:215], v[124:127]
	v_mfma_f32_16x16x32_bf16 v[112:115], v[168:171], v[220:223], v[112:115]
	v_mfma_f32_16x16x32_bf16 v[108:111], v[178:181], v[220:223], v[108:111]
	v_mfma_f32_16x16x32_bf16 v[88:91], v[168:171], v[228:231], v[88:91]
	v_mfma_f32_16x16x32_bf16 v[96:99], v[178:181], v[228:231], v[96:99]
	v_mfma_f32_16x16x32_bf16 v[80:83], v[168:171], v[236:239], v[80:83]
	v_mfma_f32_16x16x32_bf16 v[76:79], v[178:181], v[236:239], v[76:79]
	v_mfma_f32_16x16x32_bf16 v[116:119], v[182:185], v[208:211], v[116:119]
	v_mfma_f32_16x16x32_bf16 v[120:123], v[200:203], v[208:211], v[120:123]
	v_mfma_f32_16x16x32_bf16 v[100:103], v[182:185], v[216:219], v[100:103]
	v_mfma_f32_16x16x32_bf16 v[104:107], v[200:203], v[216:219], v[104:107]
	v_mfma_f32_16x16x32_bf16 v[84:87], v[182:185], v[224:227], v[84:87]
	v_mfma_f32_16x16x32_bf16 v[92:95], v[200:203], v[224:227], v[92:95]
	v_mfma_f32_16x16x32_bf16 v[68:71], v[182:185], v[232:235], v[68:71]
	v_mfma_f32_16x16x32_bf16 v[72:75], v[200:203], v[232:235], v[72:75]
	v_mfma_f32_16x16x32_bf16 v[116:119], v[186:189], v[212:215], v[116:119]
	v_mfma_f32_16x16x32_bf16 v[120:123], v[204:207], v[212:215], v[120:123]
	v_mfma_f32_16x16x32_bf16 v[100:103], v[186:189], v[220:223], v[100:103]
	v_mfma_f32_16x16x32_bf16 v[104:107], v[204:207], v[220:223], v[104:107]
	v_mfma_f32_16x16x32_bf16 v[84:87], v[186:189], v[228:231], v[84:87]
	v_mfma_f32_16x16x32_bf16 v[92:95], v[204:207], v[228:231], v[92:95]
	v_mfma_f32_16x16x32_bf16 v[68:71], v[186:189], v[236:239], v[68:71]
	v_mfma_f32_16x16x32_bf16 v[72:75], v[204:207], v[236:239], v[72:75]
	s_barrier
	s_add_i32 s79, s80, s55
	v_lshl_add_u64 v[164:165], s[70:71], 0, v[2:3]
	s_mov_b32 m0, s79
	ds_read_b128 v[208:211], v158 offset:16384
	ds_read_b128 v[212:215], v158 offset:17408
	ds_read_b128 v[216:219], v158 offset:18432
	ds_read_b128 v[220:223], v158 offset:19456
	ds_read_b128 v[224:227], v158 offset:20480
	ds_read_b128 v[228:231], v158 offset:21504
	ds_read_b128 v[232:235], v158 offset:22528
	ds_read_b128 v[236:239], v158 offset:23552
	global_load_lds_dwordx4 v[164:165], off
	s_add_i32 m0, s79, 0x2000
	s_add_u32 s82, s70, 0x40000
	v_lshl_add_u64 v[240:241], s[70:71], 0, v[136:137]
	s_addc_u32 s83, s71, 0
	s_add_i32 s33, s33, s55
	global_load_lds_dwordx4 v[240:241], off
	v_lshl_add_u64 v[242:243], s[82:83], 0, v[2:3]
	s_mov_b32 m0, s33
	v_lshl_add_u64 v[244:245], s[72:73], 0, v[134:135]
	global_load_lds_dwordx4 v[242:243], off
	v_lshl_add_u64 v[242:243], s[82:83], 0, v[136:137]
	s_add_i32 m0, s33, 0x2000
	s_nop 0
	global_load_lds_dwordx4 v[242:243], off
	v_lshl_add_u64 v[242:243], s[72:73], 0, v[132:133]
	s_mov_b32 m0, s3
	s_nop 0
	global_load_lds_dwordx4 v[242:243], off
	s_mov_b32 m0, s24
	s_nop 0
	global_load_lds_dwordx4 v[244:245], off
	s_waitcnt vmcnt(8)
	s_waitcnt lgkmcnt(0)
	s_barrier
	s_waitcnt lgkmcnt(0)
	v_mfma_f32_16x16x32_bf16 v[64:67], v[160:163], v[208:211], v[64:67]
	v_mfma_f32_16x16x32_bf16 v[60:63], v[174:177], v[208:211], v[60:63]
	v_mfma_f32_16x16x32_bf16 v[48:51], v[160:163], v[216:219], v[48:51]
	v_mfma_f32_16x16x32_bf16 v[44:47], v[174:177], v[216:219], v[44:47]
	v_mfma_f32_16x16x32_bf16 v[32:35], v[160:163], v[224:227], v[32:35]
	v_mfma_f32_16x16x32_bf16 v[28:31], v[174:177], v[224:227], v[28:31]
	v_mfma_f32_16x16x32_bf16 v[16:19], v[160:163], v[232:235], v[16:19]
	v_mfma_f32_16x16x32_bf16 v[12:15], v[174:177], v[232:235], v[12:15]
	v_mfma_f32_16x16x32_bf16 v[64:67], v[168:171], v[212:215], v[64:67]
	v_mfma_f32_16x16x32_bf16 v[60:63], v[178:181], v[212:215], v[60:63]
	v_mfma_f32_16x16x32_bf16 v[48:51], v[168:171], v[220:223], v[48:51]
	v_mfma_f32_16x16x32_bf16 v[44:47], v[178:181], v[220:223], v[44:47]
	v_mfma_f32_16x16x32_bf16 v[32:35], v[168:171], v[228:231], v[32:35]
	v_mfma_f32_16x16x32_bf16 v[28:31], v[178:181], v[228:231], v[28:31]
	v_mfma_f32_16x16x32_bf16 v[16:19], v[168:171], v[236:239], v[16:19]
	v_mfma_f32_16x16x32_bf16 v[12:15], v[178:181], v[236:239], v[12:15]
	v_mfma_f32_16x16x32_bf16 v[52:55], v[182:185], v[208:211], v[52:55]
	v_mfma_f32_16x16x32_bf16 v[56:59], v[200:203], v[208:211], v[56:59]
	v_mfma_f32_16x16x32_bf16 v[36:39], v[182:185], v[216:219], v[36:39]
	v_mfma_f32_16x16x32_bf16 v[40:43], v[200:203], v[216:219], v[40:43]
	v_mfma_f32_16x16x32_bf16 v[20:23], v[182:185], v[224:227], v[20:23]
	v_mfma_f32_16x16x32_bf16 v[24:27], v[200:203], v[224:227], v[24:27]
	v_mfma_f32_16x16x32_bf16 v[4:7], v[182:185], v[232:235], v[4:7]
	v_mfma_f32_16x16x32_bf16 v[8:11], v[200:203], v[232:235], v[8:11]
	v_mfma_f32_16x16x32_bf16 v[52:55], v[186:189], v[212:215], v[52:55]
	v_mfma_f32_16x16x32_bf16 v[56:59], v[204:207], v[212:215], v[56:59]
	v_mfma_f32_16x16x32_bf16 v[36:39], v[186:189], v[220:223], v[36:39]
	v_mfma_f32_16x16x32_bf16 v[40:43], v[204:207], v[220:223], v[40:43]
	v_mfma_f32_16x16x32_bf16 v[20:23], v[186:189], v[228:231], v[20:23]
	v_mfma_f32_16x16x32_bf16 v[24:27], v[204:207], v[228:231], v[24:27]
	v_mfma_f32_16x16x32_bf16 v[4:7], v[186:189], v[236:239], v[4:7]
	v_mfma_f32_16x16x32_bf16 v[8:11], v[204:207], v[236:239], v[8:11]
	s_barrier
	s_add_i32 s33, 0, 0x18000
	v_add_u32_e32 v159, s33, v156
	s_add_i32 s79, 0, 0x1c000
	ds_read_b128 v[160:163], v159
	ds_read_b128 v[168:171], v159 offset:1024
	ds_read_b128 v[174:177], v159 offset:2048
	ds_read_b128 v[178:181], v159 offset:3072
	v_add_u32_e32 v159, s79, v156
	ds_read_b128 v[182:185], v159
	ds_read_b128 v[186:189], v159 offset:1024
	ds_read_b128 v[200:203], v159 offset:2048
	ds_read_b128 v[204:207], v159 offset:3072
	s_add_u32 s72, s72, 0x40000
	s_addc_u32 s73, s73, 0
	s_mov_b32 m0, s56
	v_lshl_add_u64 v[246:247], s[72:73], 0, v[132:133]
	ds_read_b128 v[208:211], v158 offset:32768
	ds_read_b128 v[212:215], v158 offset:33792
	ds_read_b128 v[216:219], v158 offset:34816
	ds_read_b128 v[220:223], v158 offset:35840
	ds_read_b128 v[224:227], v158 offset:36864
	ds_read_b128 v[228:231], v158 offset:37888
	ds_read_b128 v[232:235], v158 offset:38912
	ds_read_b128 v[236:239], v158 offset:39936
	global_load_lds_dwordx4 v[246:247], off
	v_lshl_add_u64 v[246:247], s[72:73], 0, v[134:135]
	s_mov_b32 m0, s57
	s_nop 0
	global_load_lds_dwordx4 v[246:247], off
	s_waitcnt vmcnt(8)
	s_waitcnt lgkmcnt(0)
	s_barrier
	s_waitcnt lgkmcnt(0)
	v_mfma_f32_16x16x32_bf16 v[128:131], v[160:163], v[208:211], v[128:131]
	v_mfma_f32_16x16x32_bf16 v[124:127], v[174:177], v[208:211], v[124:127]
	v_mfma_f32_16x16x32_bf16 v[112:115], v[160:163], v[216:219], v[112:115]
	v_mfma_f32_16x16x32_bf16 v[108:111], v[174:177], v[216:219], v[108:111]
	v_mfma_f32_16x16x32_bf16 v[88:91], v[160:163], v[224:227], v[88:91]
	v_mfma_f32_16x16x32_bf16 v[96:99], v[174:177], v[224:227], v[96:99]
	v_mfma_f32_16x16x32_bf16 v[80:83], v[160:163], v[232:235], v[80:83]
	v_mfma_f32_16x16x32_bf16 v[76:79], v[174:177], v[232:235], v[76:79]
	v_mfma_f32_16x16x32_bf16 v[128:131], v[168:171], v[212:215], v[128:131]
	v_mfma_f32_16x16x32_bf16 v[124:127], v[178:181], v[212:215], v[124:127]
	v_mfma_f32_16x16x32_bf16 v[112:115], v[168:171], v[220:223], v[112:115]
	v_mfma_f32_16x16x32_bf16 v[108:111], v[178:181], v[220:223], v[108:111]
	v_mfma_f32_16x16x32_bf16 v[88:91], v[168:171], v[228:231], v[88:91]
	v_mfma_f32_16x16x32_bf16 v[96:99], v[178:181], v[228:231], v[96:99]
	v_mfma_f32_16x16x32_bf16 v[80:83], v[168:171], v[236:239], v[80:83]
	v_mfma_f32_16x16x32_bf16 v[76:79], v[178:181], v[236:239], v[76:79]
	v_mfma_f32_16x16x32_bf16 v[116:119], v[182:185], v[208:211], v[116:119]
	v_mfma_f32_16x16x32_bf16 v[120:123], v[200:203], v[208:211], v[120:123]
	v_mfma_f32_16x16x32_bf16 v[100:103], v[182:185], v[216:219], v[100:103]
	v_mfma_f32_16x16x32_bf16 v[104:107], v[200:203], v[216:219], v[104:107]
	v_mfma_f32_16x16x32_bf16 v[84:87], v[182:185], v[224:227], v[84:87]
	v_mfma_f32_16x16x32_bf16 v[92:95], v[200:203], v[224:227], v[92:95]
	v_mfma_f32_16x16x32_bf16 v[68:71], v[182:185], v[232:235], v[68:71]
	v_mfma_f32_16x16x32_bf16 v[72:75], v[200:203], v[232:235], v[72:75]
	v_mfma_f32_16x16x32_bf16 v[116:119], v[186:189], v[212:215], v[116:119]
	v_mfma_f32_16x16x32_bf16 v[120:123], v[204:207], v[212:215], v[120:123]
	v_mfma_f32_16x16x32_bf16 v[100:103], v[186:189], v[220:223], v[100:103]
	v_mfma_f32_16x16x32_bf16 v[104:107], v[204:207], v[220:223], v[104:107]
	v_mfma_f32_16x16x32_bf16 v[84:87], v[186:189], v[228:231], v[84:87]
	v_mfma_f32_16x16x32_bf16 v[92:95], v[204:207], v[228:231], v[92:95]
	v_mfma_f32_16x16x32_bf16 v[68:71], v[186:189], v[236:239], v[68:71]
	v_mfma_f32_16x16x32_bf16 v[72:75], v[204:207], v[236:239], v[72:75]
	s_barrier
	s_add_i32 s33, s33, s55
	v_lshl_add_u64 v[164:165], v[164:165], 0, s[30:31]
	s_mov_b32 m0, s33
	ds_read_b128 v[208:211], v158 offset:49152
	ds_read_b128 v[212:215], v158 offset:50176
	ds_read_b128 v[216:219], v158 offset:51200
	ds_read_b128 v[220:223], v158 offset:52224
	ds_read_b128 v[224:227], v158 offset:53248
	ds_read_b128 v[228:231], v158 offset:54272
	ds_read_b128 v[232:235], v158 offset:55296
	ds_read_b128 v[236:239], v158 offset:56320
	global_load_lds_dwordx4 v[164:165], off
	s_add_i32 m0, s33, 0x2000
	s_add_u32 s70, s70, 0x40080
	v_lshl_add_u64 v[164:165], v[240:241], 0, s[30:31]
	s_addc_u32 s71, s71, 0
	s_add_i32 s33, s79, s55
	global_load_lds_dwordx4 v[164:165], off
	v_lshl_add_u64 v[164:165], s[70:71], 0, v[2:3]
	s_mov_b32 m0, s33
	s_nop 0
	global_load_lds_dwordx4 v[164:165], off
	v_lshl_add_u64 v[164:165], s[70:71], 0, v[136:137]
	s_add_i32 m0, s33, 0x2000
	s_nop 0
	global_load_lds_dwordx4 v[164:165], off
	v_lshl_add_u64 v[164:165], v[242:243], 0, s[30:31]
	s_mov_b32 m0, s10
	s_nop 0
	global_load_lds_dwordx4 v[164:165], off
	v_lshl_add_u64 v[164:165], v[244:245], 0, s[30:31]
	s_mov_b32 m0, s11
	s_nop 0
	global_load_lds_dwordx4 v[164:165], off
	s_waitcnt vmcnt(8)
	s_waitcnt lgkmcnt(0)
	s_barrier
	s_waitcnt lgkmcnt(0)
	v_mfma_f32_16x16x32_bf16 v[64:67], v[160:163], v[208:211], v[64:67]
	v_mfma_f32_16x16x32_bf16 v[60:63], v[174:177], v[208:211], v[60:63]
	v_mfma_f32_16x16x32_bf16 v[48:51], v[160:163], v[216:219], v[48:51]
	v_mfma_f32_16x16x32_bf16 v[44:47], v[174:177], v[216:219], v[44:47]
	v_mfma_f32_16x16x32_bf16 v[32:35], v[160:163], v[224:227], v[32:35]
	v_mfma_f32_16x16x32_bf16 v[28:31], v[174:177], v[224:227], v[28:31]
	v_mfma_f32_16x16x32_bf16 v[16:19], v[160:163], v[232:235], v[16:19]
	v_mfma_f32_16x16x32_bf16 v[12:15], v[174:177], v[232:235], v[12:15]
	v_mfma_f32_16x16x32_bf16 v[64:67], v[168:171], v[212:215], v[64:67]
	v_mfma_f32_16x16x32_bf16 v[60:63], v[178:181], v[212:215], v[60:63]
	v_mfma_f32_16x16x32_bf16 v[48:51], v[168:171], v[220:223], v[48:51]
	v_mfma_f32_16x16x32_bf16 v[44:47], v[178:181], v[220:223], v[44:47]
	v_mfma_f32_16x16x32_bf16 v[32:35], v[168:171], v[228:231], v[32:35]
	v_mfma_f32_16x16x32_bf16 v[28:31], v[178:181], v[228:231], v[28:31]
	v_mfma_f32_16x16x32_bf16 v[16:19], v[168:171], v[236:239], v[16:19]
	v_mfma_f32_16x16x32_bf16 v[12:15], v[178:181], v[236:239], v[12:15]
	v_mfma_f32_16x16x32_bf16 v[52:55], v[182:185], v[208:211], v[52:55]
	v_mfma_f32_16x16x32_bf16 v[56:59], v[200:203], v[208:211], v[56:59]
	v_mfma_f32_16x16x32_bf16 v[36:39], v[182:185], v[216:219], v[36:39]
	v_mfma_f32_16x16x32_bf16 v[40:43], v[200:203], v[216:219], v[40:43]
	v_mfma_f32_16x16x32_bf16 v[20:23], v[182:185], v[224:227], v[20:23]
	v_mfma_f32_16x16x32_bf16 v[24:27], v[200:203], v[224:227], v[24:27]
	v_mfma_f32_16x16x32_bf16 v[4:7], v[182:185], v[232:235], v[4:7]
	v_mfma_f32_16x16x32_bf16 v[8:11], v[200:203], v[232:235], v[8:11]
	v_mfma_f32_16x16x32_bf16 v[52:55], v[186:189], v[212:215], v[52:55]
	v_mfma_f32_16x16x32_bf16 v[56:59], v[204:207], v[212:215], v[56:59]
	v_mfma_f32_16x16x32_bf16 v[36:39], v[186:189], v[220:223], v[36:39]
	v_mfma_f32_16x16x32_bf16 v[40:43], v[204:207], v[220:223], v[40:43]
	v_mfma_f32_16x16x32_bf16 v[20:23], v[186:189], v[228:231], v[20:23]
	v_mfma_f32_16x16x32_bf16 v[24:27], v[204:207], v[228:231], v[24:27]
	v_mfma_f32_16x16x32_bf16 v[4:7], v[186:189], v[236:239], v[4:7]
	v_mfma_f32_16x16x32_bf16 v[8:11], v[204:207], v[236:239], v[8:11]
	s_barrier
	s_add_i32 s6, s6, 2
	s_add_u32 s12, s12, 0x100
	s_addc_u32 s13, s13, 0
	s_cmp_gt_u32 s6, 13
	s_cbranch_scc0 .LBB0_604
	v_cndmask_b32_e64 v142, 0, 1, s[14:15]
	v_cmp_ne_u32_e64 s[12:13], 1, v142
	s_andn2_b64 vcc, exec, s[14:15]
	s_mov_b64 s[14:15], -1
	s_cbranch_vccnz .LBB0_607
	s_add_u32 s70, s75, 0xffffff00
	s_addc_u32 s71, s76, -1
	s_cbranch_execnz .LBB0_596
	s_branch .LBB0_608

.LBB0_664:
	s_add_u32 s6, s68, 0xfffc0080
	s_addc_u32 s33, s69, -1
	s_add_i32 s82, 0, 0x10000
	s_cmp_eq_u32 s80, 12
	s_cselect_b32 s73, s10, s33
	s_cselect_b32 s72, s11, s6
	v_add_u32_e32 v2, s82, v148
	s_cselect_b32 s71, s15, s67
	s_cselect_b32 s70, s59, s61
	s_add_i32 s6, 0, 0x14000
	ds_read_b128 v[152:155], v2
	ds_read_b128 v[156:159], v2 offset:1024
	ds_read_b128 v[160:163], v2 offset:2048
	ds_read_b128 v[168:171], v2 offset:3072
	v_add_u32_e32 v2, s6, v148
	ds_read_b128 v[174:177], v2
	ds_read_b128 v[178:181], v2 offset:1024
	ds_read_b128 v[182:185], v2 offset:2048
	ds_read_b128 v[186:189], v2 offset:3072
	v_lshl_add_u64 v[146:147], s[68:69], 0, v[142:143]
	s_add_i32 m0, s35, 0xc000
	ds_read_b128 v[200:203], v151
	ds_read_b128 v[204:207], v151 offset:1024
	ds_read_b128 v[208:211], v151 offset:2048
	ds_read_b128 v[212:215], v151 offset:3072
	ds_read_b128 v[216:219], v151 offset:4096
	ds_read_b128 v[220:223], v151 offset:5120
	ds_read_b128 v[224:227], v151 offset:6144
	ds_read_b128 v[228:231], v151 offset:7168
	global_load_lds_dwordx4 v[146:147], off
	v_lshl_add_u64 v[146:147], s[68:69], 0, v[144:145]
	s_add_i32 m0, s35, 0xe000
	s_nop 0
	global_load_lds_dwordx4 v[146:147], off
	s_waitcnt vmcnt(8)
	s_waitcnt lgkmcnt(0)
	s_barrier
	s_waitcnt lgkmcnt(0)
	v_mfma_f32_16x16x32_bf16 v[128:131], v[152:155], v[200:203], v[128:131]
	v_mfma_f32_16x16x32_bf16 v[120:123], v[160:163], v[200:203], v[120:123]
	v_mfma_f32_16x16x32_bf16 v[112:115], v[152:155], v[208:211], v[112:115]
	v_mfma_f32_16x16x32_bf16 v[104:107], v[160:163], v[208:211], v[104:107]
	v_mfma_f32_16x16x32_bf16 v[96:99], v[152:155], v[216:219], v[96:99]
	v_mfma_f32_16x16x32_bf16 v[88:91], v[160:163], v[216:219], v[88:91]
	v_mfma_f32_16x16x32_bf16 v[80:83], v[152:155], v[224:227], v[80:83]
	v_mfma_f32_16x16x32_bf16 v[72:75], v[160:163], v[224:227], v[72:75]
	v_mfma_f32_16x16x32_bf16 v[128:131], v[156:159], v[204:207], v[128:131]
	v_mfma_f32_16x16x32_bf16 v[120:123], v[168:171], v[204:207], v[120:123]
	v_mfma_f32_16x16x32_bf16 v[112:115], v[156:159], v[212:215], v[112:115]
	v_mfma_f32_16x16x32_bf16 v[104:107], v[168:171], v[212:215], v[104:107]
	v_mfma_f32_16x16x32_bf16 v[96:99], v[156:159], v[220:223], v[96:99]
	v_mfma_f32_16x16x32_bf16 v[88:91], v[168:171], v[220:223], v[88:91]
	v_mfma_f32_16x16x32_bf16 v[80:83], v[156:159], v[228:231], v[80:83]
	v_mfma_f32_16x16x32_bf16 v[72:75], v[168:171], v[228:231], v[72:75]
	v_mfma_f32_16x16x32_bf16 v[124:127], v[174:177], v[200:203], v[124:127]
	v_mfma_f32_16x16x32_bf16 v[116:119], v[182:185], v[200:203], v[116:119]
	v_mfma_f32_16x16x32_bf16 v[108:111], v[174:177], v[208:211], v[108:111]
	v_mfma_f32_16x16x32_bf16 v[100:103], v[182:185], v[208:211], v[100:103]
	v_mfma_f32_16x16x32_bf16 v[92:95], v[174:177], v[216:219], v[92:95]
	v_mfma_f32_16x16x32_bf16 v[84:87], v[182:185], v[216:219], v[84:87]
	v_mfma_f32_16x16x32_bf16 v[76:79], v[174:177], v[224:227], v[76:79]
	v_mfma_f32_16x16x32_bf16 v[68:71], v[182:185], v[224:227], v[68:71]
	v_mfma_f32_16x16x32_bf16 v[124:127], v[178:181], v[204:207], v[124:127]
	v_mfma_f32_16x16x32_bf16 v[116:119], v[186:189], v[204:207], v[116:119]
	v_mfma_f32_16x16x32_bf16 v[108:111], v[178:181], v[212:215], v[108:111]
	v_mfma_f32_16x16x32_bf16 v[100:103], v[186:189], v[212:215], v[100:103]
	v_mfma_f32_16x16x32_bf16 v[92:95], v[178:181], v[220:223], v[92:95]
	v_mfma_f32_16x16x32_bf16 v[84:87], v[186:189], v[220:223], v[84:87]
	v_mfma_f32_16x16x32_bf16 v[76:79], v[178:181], v[228:231], v[76:79]
	v_mfma_f32_16x16x32_bf16 v[68:71], v[186:189], v[228:231], v[68:71]
	s_barrier
	s_add_i32 s33, s82, s20
	v_lshl_add_u64 v[146:147], s[70:71], 0, v[134:135]
	s_mov_b32 m0, s33
	ds_read_b128 v[200:203], v151 offset:16384
	ds_read_b128 v[204:207], v151 offset:17408
	ds_read_b128 v[208:211], v151 offset:18432
	ds_read_b128 v[212:215], v151 offset:19456
	ds_read_b128 v[216:219], v151 offset:20480
	ds_read_b128 v[220:223], v151 offset:21504
	ds_read_b128 v[224:227], v151 offset:22528
	ds_read_b128 v[228:231], v151 offset:23552
	global_load_lds_dwordx4 v[146:147], off
	s_add_i32 m0, s33, 0x2000
	s_add_u32 s82, s70, 0x40000
	v_lshl_add_u64 v[164:165], s[70:71], 0, v[138:139]
	s_addc_u32 s83, s71, 0
	s_add_i32 s6, s6, s20
	global_load_lds_dwordx4 v[164:165], off
	v_lshl_add_u64 v[232:233], s[82:83], 0, v[134:135]
	s_mov_b32 m0, s6
	v_lshl_add_u64 v[234:235], s[72:73], 0, v[136:137]
	global_load_lds_dwordx4 v[232:233], off
	v_lshl_add_u64 v[232:233], s[82:83], 0, v[138:139]
	s_add_i32 m0, s6, 0x2000
	s_nop 0
	global_load_lds_dwordx4 v[232:233], off
	v_lshl_add_u64 v[232:233], s[72:73], 0, v[132:133]
	s_mov_b32 m0, s35
	s_nop 0
	global_load_lds_dwordx4 v[232:233], off
	s_mov_b32 m0, s54
	s_nop 0
	global_load_lds_dwordx4 v[234:235], off
	s_waitcnt vmcnt(8)
	s_waitcnt lgkmcnt(0)
	s_barrier
	s_waitcnt lgkmcnt(0)
	v_mfma_f32_16x16x32_bf16 v[64:67], v[152:155], v[200:203], v[64:67]
	v_mfma_f32_16x16x32_bf16 v[56:59], v[160:163], v[200:203], v[56:59]
	v_mfma_f32_16x16x32_bf16 v[48:51], v[152:155], v[208:211], v[48:51]
	v_mfma_f32_16x16x32_bf16 v[40:43], v[160:163], v[208:211], v[40:43]
	v_mfma_f32_16x16x32_bf16 v[32:35], v[152:155], v[216:219], v[32:35]
	v_mfma_f32_16x16x32_bf16 v[24:27], v[160:163], v[216:219], v[24:27]
	v_mfma_f32_16x16x32_bf16 v[16:19], v[152:155], v[224:227], v[16:19]
	v_mfma_f32_16x16x32_bf16 v[8:11], v[160:163], v[224:227], v[8:11]
	v_mfma_f32_16x16x32_bf16 v[64:67], v[156:159], v[204:207], v[64:67]
	v_mfma_f32_16x16x32_bf16 v[56:59], v[168:171], v[204:207], v[56:59]
	v_mfma_f32_16x16x32_bf16 v[48:51], v[156:159], v[212:215], v[48:51]
	v_mfma_f32_16x16x32_bf16 v[40:43], v[168:171], v[212:215], v[40:43]
	v_mfma_f32_16x16x32_bf16 v[32:35], v[156:159], v[220:223], v[32:35]
	v_mfma_f32_16x16x32_bf16 v[24:27], v[168:171], v[220:223], v[24:27]
	v_mfma_f32_16x16x32_bf16 v[16:19], v[156:159], v[228:231], v[16:19]
	v_mfma_f32_16x16x32_bf16 v[8:11], v[168:171], v[228:231], v[8:11]
	v_mfma_f32_16x16x32_bf16 v[60:63], v[174:177], v[200:203], v[60:63]
	v_mfma_f32_16x16x32_bf16 v[52:55], v[182:185], v[200:203], v[52:55]
	v_mfma_f32_16x16x32_bf16 v[44:47], v[174:177], v[208:211], v[44:47]
	v_mfma_f32_16x16x32_bf16 v[36:39], v[182:185], v[208:211], v[36:39]
	v_mfma_f32_16x16x32_bf16 v[28:31], v[174:177], v[216:219], v[28:31]
	v_mfma_f32_16x16x32_bf16 v[20:23], v[182:185], v[216:219], v[20:23]
	v_mfma_f32_16x16x32_bf16 v[12:15], v[174:177], v[224:227], v[12:15]
	v_mfma_f32_16x16x32_bf16 v[4:7], v[182:185], v[224:227], v[4:7]
	v_mfma_f32_16x16x32_bf16 v[60:63], v[178:181], v[204:207], v[60:63]
	v_mfma_f32_16x16x32_bf16 v[52:55], v[186:189], v[204:207], v[52:55]
	v_mfma_f32_16x16x32_bf16 v[44:47], v[178:181], v[212:215], v[44:47]
	v_mfma_f32_16x16x32_bf16 v[36:39], v[186:189], v[212:215], v[36:39]
	v_mfma_f32_16x16x32_bf16 v[28:31], v[178:181], v[220:223], v[28:31]
	v_mfma_f32_16x16x32_bf16 v[20:23], v[186:189], v[220:223], v[20:23]
	v_mfma_f32_16x16x32_bf16 v[12:15], v[178:181], v[228:231], v[12:15]
	v_mfma_f32_16x16x32_bf16 v[4:7], v[186:189], v[228:231], v[4:7]
	s_barrier
	s_add_i32 s6, 0, 0x18000
	v_add_u32_e32 v2, s6, v148
	s_add_i32 s33, 0, 0x1c000
	ds_read_b128 v[152:155], v2
	ds_read_b128 v[156:159], v2 offset:1024
	ds_read_b128 v[160:163], v2 offset:2048
	ds_read_b128 v[168:171], v2 offset:3072
	v_add_u32_e32 v2, s33, v148
	ds_read_b128 v[174:177], v2
	ds_read_b128 v[178:181], v2 offset:1024
	ds_read_b128 v[182:185], v2 offset:2048
	ds_read_b128 v[186:189], v2 offset:3072
	s_add_u32 s72, s72, 0x40000
	s_addc_u32 s73, s73, 0
	s_mov_b32 m0, s55
	v_lshl_add_u64 v[236:237], s[72:73], 0, v[132:133]
	ds_read_b128 v[200:203], v151 offset:32768
	ds_read_b128 v[204:207], v151 offset:33792
	ds_read_b128 v[208:211], v151 offset:34816
	ds_read_b128 v[212:215], v151 offset:35840
	ds_read_b128 v[216:219], v151 offset:36864
	ds_read_b128 v[220:223], v151 offset:37888
	ds_read_b128 v[224:227], v151 offset:38912
	ds_read_b128 v[228:231], v151 offset:39936
	global_load_lds_dwordx4 v[236:237], off
	v_lshl_add_u64 v[236:237], s[72:73], 0, v[136:137]
	s_mov_b32 m0, s56
	s_nop 0
	global_load_lds_dwordx4 v[236:237], off
	s_waitcnt vmcnt(8)
	s_waitcnt lgkmcnt(0)
	s_barrier
	s_waitcnt lgkmcnt(0)
	v_mfma_f32_16x16x32_bf16 v[128:131], v[152:155], v[200:203], v[128:131]
	v_mfma_f32_16x16x32_bf16 v[120:123], v[160:163], v[200:203], v[120:123]
	v_mfma_f32_16x16x32_bf16 v[112:115], v[152:155], v[208:211], v[112:115]
	v_mfma_f32_16x16x32_bf16 v[104:107], v[160:163], v[208:211], v[104:107]
	v_mfma_f32_16x16x32_bf16 v[96:99], v[152:155], v[216:219], v[96:99]
	v_mfma_f32_16x16x32_bf16 v[88:91], v[160:163], v[216:219], v[88:91]
	v_mfma_f32_16x16x32_bf16 v[80:83], v[152:155], v[224:227], v[80:83]
	v_mfma_f32_16x16x32_bf16 v[72:75], v[160:163], v[224:227], v[72:75]
	v_mfma_f32_16x16x32_bf16 v[128:131], v[156:159], v[204:207], v[128:131]
	v_mfma_f32_16x16x32_bf16 v[120:123], v[168:171], v[204:207], v[120:123]
	v_mfma_f32_16x16x32_bf16 v[112:115], v[156:159], v[212:215], v[112:115]
	v_mfma_f32_16x16x32_bf16 v[104:107], v[168:171], v[212:215], v[104:107]
	v_mfma_f32_16x16x32_bf16 v[96:99], v[156:159], v[220:223], v[96:99]
	v_mfma_f32_16x16x32_bf16 v[88:91], v[168:171], v[220:223], v[88:91]
	v_mfma_f32_16x16x32_bf16 v[80:83], v[156:159], v[228:231], v[80:83]
	v_mfma_f32_16x16x32_bf16 v[72:75], v[168:171], v[228:231], v[72:75]
	v_mfma_f32_16x16x32_bf16 v[124:127], v[174:177], v[200:203], v[124:127]
	v_mfma_f32_16x16x32_bf16 v[116:119], v[182:185], v[200:203], v[116:119]
	v_mfma_f32_16x16x32_bf16 v[108:111], v[174:177], v[208:211], v[108:111]
	v_mfma_f32_16x16x32_bf16 v[100:103], v[182:185], v[208:211], v[100:103]
	v_mfma_f32_16x16x32_bf16 v[92:95], v[174:177], v[216:219], v[92:95]
	v_mfma_f32_16x16x32_bf16 v[84:87], v[182:185], v[216:219], v[84:87]
	v_mfma_f32_16x16x32_bf16 v[76:79], v[174:177], v[224:227], v[76:79]
	v_mfma_f32_16x16x32_bf16 v[68:71], v[182:185], v[224:227], v[68:71]
	v_mfma_f32_16x16x32_bf16 v[124:127], v[178:181], v[204:207], v[124:127]
	v_mfma_f32_16x16x32_bf16 v[116:119], v[186:189], v[204:207], v[116:119]
	v_mfma_f32_16x16x32_bf16 v[108:111], v[178:181], v[212:215], v[108:111]
	v_mfma_f32_16x16x32_bf16 v[100:103], v[186:189], v[212:215], v[100:103]
	v_mfma_f32_16x16x32_bf16 v[92:95], v[178:181], v[220:223], v[92:95]
	v_mfma_f32_16x16x32_bf16 v[84:87], v[186:189], v[220:223], v[84:87]
	v_mfma_f32_16x16x32_bf16 v[76:79], v[178:181], v[228:231], v[76:79]
	v_mfma_f32_16x16x32_bf16 v[68:71], v[186:189], v[228:231], v[68:71]
	s_barrier
	s_add_i32 s6, s6, s20
	v_lshl_add_u64 v[146:147], v[146:147], 0, s[30:31]
	s_mov_b32 m0, s6
	ds_read_b128 v[200:203], v151 offset:49152
	ds_read_b128 v[204:207], v151 offset:50176
	ds_read_b128 v[208:211], v151 offset:51200
	ds_read_b128 v[212:215], v151 offset:52224
	ds_read_b128 v[216:219], v151 offset:53248
	ds_read_b128 v[220:223], v151 offset:54272
	ds_read_b128 v[224:227], v151 offset:55296
	ds_read_b128 v[228:231], v151 offset:56320
	global_load_lds_dwordx4 v[146:147], off
	s_add_i32 m0, s6, 0x2000
	s_add_u32 s70, s70, 0x40080
	v_lshl_add_u64 v[146:147], v[164:165], 0, s[30:31]
	s_addc_u32 s71, s71, 0
	s_add_i32 s6, s33, s20
	global_load_lds_dwordx4 v[146:147], off
	v_lshl_add_u64 v[146:147], s[70:71], 0, v[134:135]
	s_mov_b32 m0, s6
	s_nop 0
	global_load_lds_dwordx4 v[146:147], off
	v_lshl_add_u64 v[146:147], s[70:71], 0, v[138:139]
	s_add_i32 m0, s6, 0x2000
	s_nop 0
	global_load_lds_dwordx4 v[146:147], off
	v_lshl_add_u64 v[146:147], v[232:233], 0, s[30:31]
	s_mov_b32 m0, s76
	s_nop 0
	global_load_lds_dwordx4 v[146:147], off
	v_lshl_add_u64 v[146:147], v[234:235], 0, s[30:31]
	s_mov_b32 m0, s77
	s_nop 0
	global_load_lds_dwordx4 v[146:147], off
	s_waitcnt vmcnt(8)
	s_waitcnt lgkmcnt(0)
	s_barrier
	s_waitcnt lgkmcnt(0)
	v_mfma_f32_16x16x32_bf16 v[64:67], v[152:155], v[200:203], v[64:67]
	v_mfma_f32_16x16x32_bf16 v[56:59], v[160:163], v[200:203], v[56:59]
	v_mfma_f32_16x16x32_bf16 v[48:51], v[152:155], v[208:211], v[48:51]
	v_mfma_f32_16x16x32_bf16 v[40:43], v[160:163], v[208:211], v[40:43]
	v_mfma_f32_16x16x32_bf16 v[32:35], v[152:155], v[216:219], v[32:35]
	v_mfma_f32_16x16x32_bf16 v[24:27], v[160:163], v[216:219], v[24:27]
	v_mfma_f32_16x16x32_bf16 v[16:19], v[152:155], v[224:227], v[16:19]
	v_mfma_f32_16x16x32_bf16 v[8:11], v[160:163], v[224:227], v[8:11]
	v_mfma_f32_16x16x32_bf16 v[64:67], v[156:159], v[204:207], v[64:67]
	v_mfma_f32_16x16x32_bf16 v[56:59], v[168:171], v[204:207], v[56:59]
	v_mfma_f32_16x16x32_bf16 v[48:51], v[156:159], v[212:215], v[48:51]
	v_mfma_f32_16x16x32_bf16 v[40:43], v[168:171], v[212:215], v[40:43]
	v_mfma_f32_16x16x32_bf16 v[32:35], v[156:159], v[220:223], v[32:35]
	v_mfma_f32_16x16x32_bf16 v[24:27], v[168:171], v[220:223], v[24:27]
	v_mfma_f32_16x16x32_bf16 v[16:19], v[156:159], v[228:231], v[16:19]
	v_mfma_f32_16x16x32_bf16 v[8:11], v[168:171], v[228:231], v[8:11]
	v_mfma_f32_16x16x32_bf16 v[60:63], v[174:177], v[200:203], v[60:63]
	v_mfma_f32_16x16x32_bf16 v[52:55], v[182:185], v[200:203], v[52:55]
	v_mfma_f32_16x16x32_bf16 v[44:47], v[174:177], v[208:211], v[44:47]
	v_mfma_f32_16x16x32_bf16 v[36:39], v[182:185], v[208:211], v[36:39]
	v_mfma_f32_16x16x32_bf16 v[28:31], v[174:177], v[216:219], v[28:31]
	v_mfma_f32_16x16x32_bf16 v[20:23], v[182:185], v[216:219], v[20:23]
	v_mfma_f32_16x16x32_bf16 v[12:15], v[174:177], v[224:227], v[12:15]
	v_mfma_f32_16x16x32_bf16 v[4:7], v[182:185], v[224:227], v[4:7]
	v_mfma_f32_16x16x32_bf16 v[60:63], v[178:181], v[204:207], v[60:63]
	v_mfma_f32_16x16x32_bf16 v[52:55], v[186:189], v[204:207], v[52:55]
	v_mfma_f32_16x16x32_bf16 v[44:47], v[178:181], v[212:215], v[44:47]
	v_mfma_f32_16x16x32_bf16 v[36:39], v[186:189], v[212:215], v[36:39]
	v_mfma_f32_16x16x32_bf16 v[28:31], v[178:181], v[220:223], v[28:31]
	v_mfma_f32_16x16x32_bf16 v[20:23], v[186:189], v[220:223], v[20:23]
	v_mfma_f32_16x16x32_bf16 v[12:15], v[178:181], v[228:231], v[12:15]
	v_mfma_f32_16x16x32_bf16 v[4:7], v[186:189], v[228:231], v[4:7]
	s_barrier
	s_add_i32 s80, s80, 2
	s_add_u32 s68, s68, 0x100
	s_addc_u32 s69, s69, 0
	s_add_u32 s61, s61, 0x100
	s_addc_u32 s67, s67, 0
	s_cmp_gt_u32 s80, 13
	s_cbranch_scc0 .LBB0_664
	s_and_b64 vcc, exec, s[18:19]
	s_cbranch_vccz .LBB0_667
	s_barrier

.LBB0_834:
	s_add_u32 s33, s68, s12
	s_addc_u32 s74, s69, s13
	s_cmp_eq_u32 s89, 40
	s_cselect_b32 s78, s82, s33
	s_cselect_b32 s79, s65, s74
	s_cselect_b32 s76, s83, s6
	s_cselect_b32 s77, s63, s84
	s_add_u32 s74, s78, 0x200000
	s_addc_u32 s75, s79, 0
	s_add_i32 s33, 0, 0x10000
	v_add_u32_e32 v159, s33, v156
	s_add_i32 s97, 0, 0x14000
	ds_read_b128 v[160:163], v159
	ds_read_b128 v[168:171], v159 offset:1024
	ds_read_b128 v[174:177], v159 offset:2048
	ds_read_b128 v[178:181], v159 offset:3072
	v_add_u32_e32 v159, s97, v156
	ds_read_b128 v[182:185], v159
	ds_read_b128 v[186:189], v159 offset:1024
	ds_read_b128 v[200:203], v159 offset:2048
	ds_read_b128 v[204:207], v159 offset:3072
	v_lshl_add_u64 v[164:165], s[68:69], 0, v[144:145]
	s_add_i32 m0, s24, 0xc000
	ds_read_b128 v[208:211], v158
	ds_read_b128 v[212:215], v158 offset:1024
	ds_read_b128 v[216:219], v158 offset:2048
	ds_read_b128 v[220:223], v158 offset:3072
	ds_read_b128 v[224:227], v158 offset:4096
	ds_read_b128 v[228:231], v158 offset:5120
	ds_read_b128 v[232:235], v158 offset:6144
	ds_read_b128 v[236:239], v158 offset:7168
	global_load_lds_dwordx4 v[164:165], off
	v_lshl_add_u64 v[164:165], s[68:69], 0, v[142:143]
	s_add_i32 m0, s24, 0xe000
	s_nop 0
	global_load_lds_dwordx4 v[164:165], off
	s_waitcnt vmcnt(8)
	s_waitcnt lgkmcnt(0)
	s_barrier
	s_waitcnt lgkmcnt(0)
	v_mfma_f32_16x16x32_bf16 v[128:131], v[160:163], v[208:211], v[128:131]
	v_mfma_f32_16x16x32_bf16 v[124:127], v[174:177], v[208:211], v[124:127]
	v_mfma_f32_16x16x32_bf16 v[104:107], v[160:163], v[216:219], v[104:107]
	v_mfma_f32_16x16x32_bf16 v[100:103], v[174:177], v[216:219], v[100:103]
	v_mfma_f32_16x16x32_bf16 v[84:87], v[160:163], v[224:227], v[84:87]
	v_mfma_f32_16x16x32_bf16 v[88:91], v[174:177], v[224:227], v[88:91]
	v_mfma_f32_16x16x32_bf16 v[72:75], v[160:163], v[232:235], v[72:75]
	v_mfma_f32_16x16x32_bf16 v[68:71], v[174:177], v[232:235], v[68:71]
	v_mfma_f32_16x16x32_bf16 v[128:131], v[168:171], v[212:215], v[128:131]
	v_mfma_f32_16x16x32_bf16 v[124:127], v[178:181], v[212:215], v[124:127]
	v_mfma_f32_16x16x32_bf16 v[104:107], v[168:171], v[220:223], v[104:107]
	v_mfma_f32_16x16x32_bf16 v[100:103], v[178:181], v[220:223], v[100:103]
	v_mfma_f32_16x16x32_bf16 v[84:87], v[168:171], v[228:231], v[84:87]
	v_mfma_f32_16x16x32_bf16 v[88:91], v[178:181], v[228:231], v[88:91]
	v_mfma_f32_16x16x32_bf16 v[72:75], v[168:171], v[236:239], v[72:75]
	v_mfma_f32_16x16x32_bf16 v[68:71], v[178:181], v[236:239], v[68:71]
	v_mfma_f32_16x16x32_bf16 v[120:123], v[182:185], v[208:211], v[120:123]
	v_mfma_f32_16x16x32_bf16 v[116:119], v[200:203], v[208:211], v[116:119]
	v_mfma_f32_16x16x32_bf16 v[112:115], v[182:185], v[216:219], v[112:115]
	v_mfma_f32_16x16x32_bf16 v[108:111], v[200:203], v[216:219], v[108:111]
	v_mfma_f32_16x16x32_bf16 v[92:95], v[182:185], v[224:227], v[92:95]
	v_mfma_f32_16x16x32_bf16 v[96:99], v[200:203], v[224:227], v[96:99]
	v_mfma_f32_16x16x32_bf16 v[80:83], v[182:185], v[232:235], v[80:83]
	v_mfma_f32_16x16x32_bf16 v[76:79], v[200:203], v[232:235], v[76:79]
	v_mfma_f32_16x16x32_bf16 v[120:123], v[186:189], v[212:215], v[120:123]
	v_mfma_f32_16x16x32_bf16 v[116:119], v[204:207], v[212:215], v[116:119]
	v_mfma_f32_16x16x32_bf16 v[112:115], v[186:189], v[220:223], v[112:115]
	v_mfma_f32_16x16x32_bf16 v[108:111], v[204:207], v[220:223], v[108:111]
	v_mfma_f32_16x16x32_bf16 v[92:95], v[186:189], v[228:231], v[92:95]
	v_mfma_f32_16x16x32_bf16 v[96:99], v[204:207], v[228:231], v[96:99]
	v_mfma_f32_16x16x32_bf16 v[80:83], v[186:189], v[236:239], v[80:83]
	v_mfma_f32_16x16x32_bf16 v[76:79], v[204:207], v[236:239], v[76:79]
	s_barrier
	s_add_i32 s33, s33, s55
	v_lshl_add_u64 v[164:165], s[76:77], 0, v[2:3]
	s_mov_b32 m0, s33
	ds_read_b128 v[208:211], v158 offset:16384
	ds_read_b128 v[212:215], v158 offset:17408
	ds_read_b128 v[216:219], v158 offset:18432
	ds_read_b128 v[220:223], v158 offset:19456
	ds_read_b128 v[224:227], v158 offset:20480
	ds_read_b128 v[228:231], v158 offset:21504
	ds_read_b128 v[232:235], v158 offset:22528
	ds_read_b128 v[236:239], v158 offset:23552
	global_load_lds_dwordx4 v[164:165], off
	s_add_i32 m0, s33, 0x2000
	s_add_u32 s94, s76, 0x4000
	v_lshl_add_u64 v[164:165], s[76:77], 0, v[136:137]
	s_addc_u32 s95, s77, 0
	s_add_i32 s33, s97, s55
	global_load_lds_dwordx4 v[164:165], off
	v_lshl_add_u64 v[164:165], s[94:95], 0, v[2:3]
	s_mov_b32 m0, s33
	s_nop 0
	global_load_lds_dwordx4 v[164:165], off
	v_lshl_add_u64 v[164:165], s[94:95], 0, v[136:137]
	s_add_i32 m0, s33, 0x2000
	s_nop 0
	global_load_lds_dwordx4 v[164:165], off
	v_lshl_add_u64 v[164:165], s[78:79], 0, v[132:133]
	s_mov_b32 m0, s24
	s_nop 0
	global_load_lds_dwordx4 v[164:165], off
	v_lshl_add_u64 v[164:165], s[78:79], 0, v[134:135]
	s_mov_b32 m0, s56
	s_nop 0
	global_load_lds_dwordx4 v[164:165], off
	s_waitcnt vmcnt(8)
	s_waitcnt lgkmcnt(0)
	s_barrier
	s_waitcnt lgkmcnt(0)
	v_mfma_f32_16x16x32_bf16 v[56:59], v[160:163], v[208:211], v[56:59]
	v_mfma_f32_16x16x32_bf16 v[52:55], v[174:177], v[208:211], v[52:55]
	v_mfma_f32_16x16x32_bf16 v[40:43], v[160:163], v[216:219], v[40:43]
	v_mfma_f32_16x16x32_bf16 v[36:39], v[174:177], v[216:219], v[36:39]
	v_mfma_f32_16x16x32_bf16 v[24:27], v[160:163], v[224:227], v[24:27]
	v_mfma_f32_16x16x32_bf16 v[20:23], v[174:177], v[224:227], v[20:23]
	v_mfma_f32_16x16x32_bf16 v[8:11], v[160:163], v[232:235], v[8:11]
	v_mfma_f32_16x16x32_bf16 v[4:7], v[174:177], v[232:235], v[4:7]
	v_mfma_f32_16x16x32_bf16 v[56:59], v[168:171], v[212:215], v[56:59]
	v_mfma_f32_16x16x32_bf16 v[52:55], v[178:181], v[212:215], v[52:55]
	v_mfma_f32_16x16x32_bf16 v[40:43], v[168:171], v[220:223], v[40:43]
	v_mfma_f32_16x16x32_bf16 v[36:39], v[178:181], v[220:223], v[36:39]
	v_mfma_f32_16x16x32_bf16 v[24:27], v[168:171], v[228:231], v[24:27]
	v_mfma_f32_16x16x32_bf16 v[20:23], v[178:181], v[228:231], v[20:23]
	v_mfma_f32_16x16x32_bf16 v[8:11], v[168:171], v[236:239], v[8:11]
	v_mfma_f32_16x16x32_bf16 v[4:7], v[178:181], v[236:239], v[4:7]
	v_mfma_f32_16x16x32_bf16 v[64:67], v[182:185], v[208:211], v[64:67]
	v_mfma_f32_16x16x32_bf16 v[60:63], v[200:203], v[208:211], v[60:63]
	v_mfma_f32_16x16x32_bf16 v[48:51], v[182:185], v[216:219], v[48:51]
	v_mfma_f32_16x16x32_bf16 v[44:47], v[200:203], v[216:219], v[44:47]
	v_mfma_f32_16x16x32_bf16 v[32:35], v[182:185], v[224:227], v[32:35]
	v_mfma_f32_16x16x32_bf16 v[28:31], v[200:203], v[224:227], v[28:31]
	v_mfma_f32_16x16x32_bf16 v[12:15], v[182:185], v[232:235], v[12:15]
	v_mfma_f32_16x16x32_bf16 v[16:19], v[200:203], v[232:235], v[16:19]
	v_mfma_f32_16x16x32_bf16 v[64:67], v[186:189], v[212:215], v[64:67]
	v_mfma_f32_16x16x32_bf16 v[60:63], v[204:207], v[212:215], v[60:63]
	v_mfma_f32_16x16x32_bf16 v[48:51], v[186:189], v[220:223], v[48:51]
	v_mfma_f32_16x16x32_bf16 v[44:47], v[204:207], v[220:223], v[44:47]
	v_mfma_f32_16x16x32_bf16 v[32:35], v[186:189], v[228:231], v[32:35]
	v_mfma_f32_16x16x32_bf16 v[28:31], v[204:207], v[228:231], v[28:31]
	v_mfma_f32_16x16x32_bf16 v[12:15], v[186:189], v[236:239], v[12:15]
	v_mfma_f32_16x16x32_bf16 v[16:19], v[204:207], v[236:239], v[16:19]
	s_barrier
	s_add_i32 s33, 0, 0x18000
	v_add_u32_e32 v159, s33, v156
	s_add_i32 s94, 0, 0x1c000
	ds_read_b128 v[160:163], v159
	ds_read_b128 v[168:171], v159 offset:1024
	ds_read_b128 v[174:177], v159 offset:2048
	ds_read_b128 v[178:181], v159 offset:3072
	v_add_u32_e32 v159, s94, v156
	ds_read_b128 v[182:185], v159
	ds_read_b128 v[186:189], v159 offset:1024
	ds_read_b128 v[200:203], v159 offset:2048
	ds_read_b128 v[204:207], v159 offset:3072
	s_add_u32 s78, s78, 0x4000
	s_addc_u32 s79, s79, 0
	s_mov_b32 m0, s57
	v_lshl_add_u64 v[164:165], s[78:79], 0, v[132:133]
	ds_read_b128 v[208:211], v158 offset:32768
	ds_read_b128 v[212:215], v158 offset:33792
	ds_read_b128 v[216:219], v158 offset:34816
	ds_read_b128 v[220:223], v158 offset:35840
	ds_read_b128 v[224:227], v158 offset:36864
	ds_read_b128 v[228:231], v158 offset:37888
	ds_read_b128 v[232:235], v158 offset:38912
	ds_read_b128 v[236:239], v158 offset:39936
	global_load_lds_dwordx4 v[164:165], off
	v_lshl_add_u64 v[164:165], s[78:79], 0, v[134:135]
	s_mov_b32 m0, s59
	s_nop 0
	global_load_lds_dwordx4 v[164:165], off
	s_waitcnt vmcnt(8)
	s_waitcnt lgkmcnt(0)
	s_barrier
	s_waitcnt lgkmcnt(0)
	v_mfma_f32_16x16x32_bf16 v[128:131], v[160:163], v[208:211], v[128:131]
	v_mfma_f32_16x16x32_bf16 v[124:127], v[174:177], v[208:211], v[124:127]
	v_mfma_f32_16x16x32_bf16 v[104:107], v[160:163], v[216:219], v[104:107]
	v_mfma_f32_16x16x32_bf16 v[100:103], v[174:177], v[216:219], v[100:103]
	v_mfma_f32_16x16x32_bf16 v[84:87], v[160:163], v[224:227], v[84:87]
	v_mfma_f32_16x16x32_bf16 v[88:91], v[174:177], v[224:227], v[88:91]
	v_mfma_f32_16x16x32_bf16 v[72:75], v[160:163], v[232:235], v[72:75]
	v_mfma_f32_16x16x32_bf16 v[68:71], v[174:177], v[232:235], v[68:71]
	v_mfma_f32_16x16x32_bf16 v[128:131], v[168:171], v[212:215], v[128:131]
	v_mfma_f32_16x16x32_bf16 v[124:127], v[178:181], v[212:215], v[124:127]
	v_mfma_f32_16x16x32_bf16 v[104:107], v[168:171], v[220:223], v[104:107]
	v_mfma_f32_16x16x32_bf16 v[100:103], v[178:181], v[220:223], v[100:103]
	v_mfma_f32_16x16x32_bf16 v[84:87], v[168:171], v[228:231], v[84:87]
	v_mfma_f32_16x16x32_bf16 v[88:91], v[178:181], v[228:231], v[88:91]
	v_mfma_f32_16x16x32_bf16 v[72:75], v[168:171], v[236:239], v[72:75]
	v_mfma_f32_16x16x32_bf16 v[68:71], v[178:181], v[236:239], v[68:71]
	v_mfma_f32_16x16x32_bf16 v[120:123], v[182:185], v[208:211], v[120:123]
	v_mfma_f32_16x16x32_bf16 v[116:119], v[200:203], v[208:211], v[116:119]
	v_mfma_f32_16x16x32_bf16 v[112:115], v[182:185], v[216:219], v[112:115]
	v_mfma_f32_16x16x32_bf16 v[108:111], v[200:203], v[216:219], v[108:111]
	v_mfma_f32_16x16x32_bf16 v[92:95], v[182:185], v[224:227], v[92:95]
	v_mfma_f32_16x16x32_bf16 v[96:99], v[200:203], v[224:227], v[96:99]
	v_mfma_f32_16x16x32_bf16 v[80:83], v[182:185], v[232:235], v[80:83]
	v_mfma_f32_16x16x32_bf16 v[76:79], v[200:203], v[232:235], v[76:79]
	v_mfma_f32_16x16x32_bf16 v[120:123], v[186:189], v[212:215], v[120:123]
	v_mfma_f32_16x16x32_bf16 v[116:119], v[204:207], v[212:215], v[116:119]
	v_mfma_f32_16x16x32_bf16 v[112:115], v[186:189], v[220:223], v[112:115]
	v_mfma_f32_16x16x32_bf16 v[108:111], v[204:207], v[220:223], v[108:111]
	v_mfma_f32_16x16x32_bf16 v[92:95], v[186:189], v[228:231], v[92:95]
	v_mfma_f32_16x16x32_bf16 v[96:99], v[204:207], v[228:231], v[96:99]
	v_mfma_f32_16x16x32_bf16 v[80:83], v[186:189], v[236:239], v[80:83]
	v_mfma_f32_16x16x32_bf16 v[76:79], v[204:207], v[236:239], v[76:79]
	s_barrier
	s_add_u32 s78, s76, 0x20000
	s_addc_u32 s79, s77, 0
	s_add_i32 s33, s33, s55
	v_lshl_add_u64 v[164:165], s[78:79], 0, v[2:3]
	s_mov_b32 m0, s33
	ds_read_b128 v[208:211], v158 offset:49152
	ds_read_b128 v[212:215], v158 offset:50176
	ds_read_b128 v[216:219], v158 offset:51200
	ds_read_b128 v[220:223], v158 offset:52224
	ds_read_b128 v[224:227], v158 offset:53248
	ds_read_b128 v[228:231], v158 offset:54272
	ds_read_b128 v[232:235], v158 offset:55296
	ds_read_b128 v[236:239], v158 offset:56320
	global_load_lds_dwordx4 v[164:165], off
	s_add_i32 m0, s33, 0x2000
	s_add_u32 s76, s76, 0x24000
	v_lshl_add_u64 v[164:165], s[78:79], 0, v[136:137]
	s_addc_u32 s77, s77, 0
	s_add_i32 s33, s94, s55
	global_load_lds_dwordx4 v[164:165], off
	v_lshl_add_u64 v[164:165], s[76:77], 0, v[2:3]
	s_mov_b32 m0, s33
	s_nop 0
	global_load_lds_dwordx4 v[164:165], off
	v_lshl_add_u64 v[164:165], s[76:77], 0, v[136:137]
	s_add_i32 m0, s33, 0x2000
	s_nop 0
	global_load_lds_dwordx4 v[164:165], off
	v_lshl_add_u64 v[164:165], s[74:75], 0, v[132:133]
	s_mov_b32 m0, s10
	s_nop 0
	global_load_lds_dwordx4 v[164:165], off
	v_lshl_add_u64 v[164:165], s[74:75], 0, v[134:135]
	s_mov_b32 m0, s11
	s_nop 0
	global_load_lds_dwordx4 v[164:165], off
	s_waitcnt vmcnt(8)
	s_waitcnt lgkmcnt(0)
	s_barrier
	s_waitcnt lgkmcnt(0)
	v_mfma_f32_16x16x32_bf16 v[56:59], v[160:163], v[208:211], v[56:59]
	v_mfma_f32_16x16x32_bf16 v[52:55], v[174:177], v[208:211], v[52:55]
	v_mfma_f32_16x16x32_bf16 v[40:43], v[160:163], v[216:219], v[40:43]
	v_mfma_f32_16x16x32_bf16 v[36:39], v[174:177], v[216:219], v[36:39]
	v_mfma_f32_16x16x32_bf16 v[24:27], v[160:163], v[224:227], v[24:27]
	v_mfma_f32_16x16x32_bf16 v[20:23], v[174:177], v[224:227], v[20:23]
	v_mfma_f32_16x16x32_bf16 v[8:11], v[160:163], v[232:235], v[8:11]
	v_mfma_f32_16x16x32_bf16 v[4:7], v[174:177], v[232:235], v[4:7]
	v_mfma_f32_16x16x32_bf16 v[56:59], v[168:171], v[212:215], v[56:59]
	v_mfma_f32_16x16x32_bf16 v[52:55], v[178:181], v[212:215], v[52:55]
	v_mfma_f32_16x16x32_bf16 v[40:43], v[168:171], v[220:223], v[40:43]
	v_mfma_f32_16x16x32_bf16 v[36:39], v[178:181], v[220:223], v[36:39]
	v_mfma_f32_16x16x32_bf16 v[24:27], v[168:171], v[228:231], v[24:27]
	v_mfma_f32_16x16x32_bf16 v[20:23], v[178:181], v[228:231], v[20:23]
	v_mfma_f32_16x16x32_bf16 v[8:11], v[168:171], v[236:239], v[8:11]
	v_mfma_f32_16x16x32_bf16 v[4:7], v[178:181], v[236:239], v[4:7]
	v_mfma_f32_16x16x32_bf16 v[64:67], v[182:185], v[208:211], v[64:67]
	v_mfma_f32_16x16x32_bf16 v[60:63], v[200:203], v[208:211], v[60:63]
	v_mfma_f32_16x16x32_bf16 v[48:51], v[182:185], v[216:219], v[48:51]
	v_mfma_f32_16x16x32_bf16 v[44:47], v[200:203], v[216:219], v[44:47]
	v_mfma_f32_16x16x32_bf16 v[32:35], v[182:185], v[224:227], v[32:35]
	v_mfma_f32_16x16x32_bf16 v[28:31], v[200:203], v[224:227], v[28:31]
	v_mfma_f32_16x16x32_bf16 v[12:15], v[182:185], v[232:235], v[12:15]
	v_mfma_f32_16x16x32_bf16 v[16:19], v[200:203], v[232:235], v[16:19]
	v_mfma_f32_16x16x32_bf16 v[64:67], v[186:189], v[212:215], v[64:67]
	v_mfma_f32_16x16x32_bf16 v[60:63], v[204:207], v[212:215], v[60:63]
	v_mfma_f32_16x16x32_bf16 v[48:51], v[186:189], v[220:223], v[48:51]
	v_mfma_f32_16x16x32_bf16 v[44:47], v[204:207], v[220:223], v[44:47]
	v_mfma_f32_16x16x32_bf16 v[32:35], v[186:189], v[228:231], v[32:35]
	v_mfma_f32_16x16x32_bf16 v[28:31], v[204:207], v[228:231], v[28:31]
	v_mfma_f32_16x16x32_bf16 v[12:15], v[186:189], v[236:239], v[12:15]
	v_mfma_f32_16x16x32_bf16 v[16:19], v[204:207], v[236:239], v[16:19]
	s_barrier
	s_add_i32 s89, s89, 2
	s_add_u32 s6, s6, 0x40000
	s_addc_u32 s84, s84, 0
	s_add_u32 s12, s12, 0x400000
	s_addc_u32 s13, s13, 0
	v_lshl_add_u64 v[144:145], v[144:145], 0, s[28:29]
	s_cmp_gt_u32 s89, 41
	v_lshl_add_u64 v[142:143], v[142:143], 0, s[28:29]
	s_cbranch_scc0 .LBB0_834
	v_cndmask_b32_e64 v142, 0, 1, s[14:15]
	v_cmp_ne_u32_e64 s[12:13], 1, v142
	s_andn2_b64 vcc, exec, s[14:15]
	s_mov_b64 s[14:15], -1
	s_cbranch_vccnz .LBB0_837
	s_cbranch_execnz .LBB0_826
	s_branch .LBB0_838
